# queue pop-ahead also in the pool unit (last group's epilogue)
# baseline (speedup 1.0000x reference)
.Lpool_nz3:
	v_add_f32_e32 v93, v61, v60
	v_add_f32_e32 v93, v93, v59
	v_add_f32_e32 v93, v93, v58
	v_add_f32_e32 v93, v93, v57
	v_add_f32_e32 v93, v93, v56
	v_add_f32_e32 v93, v93, v55
	v_add_f32_e32 v93, v93, v54
	v_add_f32_e32 v93, v93, v53
	v_add_f32_e32 v93, v93, v52
	v_add_f32_e32 v93, v93, v51
	v_add_f32_e32 v93, v93, v50
	v_add_f32_e32 v93, v93, v49
	v_add_f32_e32 v93, v93, v48
	v_add_f32_e32 v93, v93, v47
	v_add_f32_e32 v93, v93, v46
	s_cmp_eq_u32 s42, 1
	s_cselect_b32 s51, 0x3f800000, s50
	v_fma_f32 v2, v93, s51, -v61
	v_add_f32_e32 v93, v93, v62
	v_sub_f32_e32 v93, v93, v46
	s_cmp_eq_u32 s42, 1
	s_cselect_b32 s51, 0x3f000000, s50
	v_fma_f32 v3, v93, s51, -v62
	v_cvt_pk_bf16_f32 v2, v2, v3
	ds_write_b16 v9, v2 offset:0
	ds_write_b16_d16_hi v9, v2 offset:144
	v_add_f32_e32 v93, v93, v63
	v_sub_f32_e32 v93, v93, v47
	s_cmp_eq_u32 s42, 1
	s_cselect_b32 s51, 0x3eaaaaab, s50
	v_fma_f32 v4, v93, s51, -v63
	v_add_f32_e32 v93, v93, v64
	v_sub_f32_e32 v93, v93, v48
	s_cmp_eq_u32 s42, 1
	s_cselect_b32 s51, 0x3e800000, s50
	v_fma_f32 v5, v93, s51, -v64
	v_cvt_pk_bf16_f32 v4, v4, v5
	ds_write_b16 v9, v4 offset:288
	ds_write_b16_d16_hi v9, v4 offset:432
	v_add_f32_e32 v93, v93, v65
	v_sub_f32_e32 v93, v93, v49
	s_cmp_eq_u32 s42, 1
	s_cselect_b32 s51, 0x3e4ccccd, s50
	v_fma_f32 v2, v93, s51, -v65
	v_add_f32_e32 v93, v93, v66
	v_sub_f32_e32 v93, v93, v50
	s_cmp_eq_u32 s42, 1
	s_cselect_b32 s51, 0x3e2aaaab, s50
	v_fma_f32 v3, v93, s51, -v66
	v_cvt_pk_bf16_f32 v2, v2, v3
	ds_write_b16 v9, v2 offset:576
	ds_write_b16_d16_hi v9, v2 offset:720
	v_add_f32_e32 v93, v93, v67
	v_sub_f32_e32 v93, v93, v51
	s_cmp_eq_u32 s42, 1
	s_cselect_b32 s51, 0x3e124925, s50
	v_fma_f32 v4, v93, s51, -v67
	v_add_f32_e32 v93, v93, v68
	v_sub_f32_e32 v93, v93, v52
	s_cmp_eq_u32 s42, 1
	s_cselect_b32 s51, 0x3e000000, s50
	v_fma_f32 v5, v93, s51, -v68
	v_cvt_pk_bf16_f32 v4, v4, v5
	ds_write_b16 v9, v4 offset:864
	ds_write_b16_d16_hi v9, v4 offset:1008
	v_add_f32_e32 v93, v93, v69
	v_sub_f32_e32 v93, v93, v53
	s_cmp_eq_u32 s42, 1
	s_cselect_b32 s51, 0x3de38e39, s50
	v_fma_f32 v2, v93, s51, -v69
	v_add_f32_e32 v93, v93, v70
	v_sub_f32_e32 v93, v93, v54
	s_cmp_eq_u32 s42, 1
	s_cselect_b32 s51, 0x3dcccccd, s50
	v_fma_f32 v3, v93, s51, -v70
	v_cvt_pk_bf16_f32 v2, v2, v3
	ds_write_b16 v9, v2 offset:1152
	ds_write_b16_d16_hi v9, v2 offset:1296
	v_add_f32_e32 v93, v93, v71
	v_sub_f32_e32 v93, v93, v55
	s_cmp_eq_u32 s42, 1
	s_cselect_b32 s51, 0x3dba2e8c, s50
	v_fma_f32 v4, v93, s51, -v71
	v_add_f32_e32 v93, v93, v72
	v_sub_f32_e32 v93, v93, v56
	s_cmp_eq_u32 s42, 1
	s_cselect_b32 s51, 0x3daaaaab, s50
	v_fma_f32 v5, v93, s51, -v72
	v_cvt_pk_bf16_f32 v4, v4, v5
	ds_write_b16 v9, v4 offset:1440
	ds_write_b16_d16_hi v9, v4 offset:1584
	v_add_f32_e32 v93, v93, v73
	v_sub_f32_e32 v93, v93, v57
	s_cmp_eq_u32 s42, 1
	s_cselect_b32 s51, 0x3d9d89d9, s50
	v_fma_f32 v2, v93, s51, -v73
	v_add_f32_e32 v93, v93, v74
	v_sub_f32_e32 v93, v93, v58
	s_cmp_eq_u32 s42, 1
	s_cselect_b32 s51, 0x3d924925, s50
	v_fma_f32 v3, v93, s51, -v74
	v_cvt_pk_bf16_f32 v2, v2, v3
	ds_write_b16 v9, v2 offset:1728
	ds_write_b16_d16_hi v9, v2 offset:1872
	v_add_f32_e32 v93, v93, v75
	v_sub_f32_e32 v93, v93, v59
	s_cmp_eq_u32 s42, 1
	s_cselect_b32 s51, 0x3d888889, s50
	v_fma_f32 v4, v93, s51, -v75
	v_add_f32_e32 v93, v93, v76
	v_sub_f32_e32 v93, v93, v60
	v_fma_f32 v5, v93, s50, -v76
	v_cvt_pk_bf16_f32 v4, v4, v5
	ds_write_b16 v9, v4 offset:2016
	ds_write_b16_d16_hi v9, v4 offset:2160
	v_add_f32_e32 v93, v93, v77
	v_sub_f32_e32 v93, v93, v61
	v_fma_f32 v2, v93, s50, -v77
	v_add_f32_e32 v93, v93, v78
	v_sub_f32_e32 v93, v93, v62
	v_fma_f32 v3, v93, s50, -v78
	v_cvt_pk_bf16_f32 v2, v2, v3
	ds_write_b16 v9, v2 offset:2304
	ds_write_b16_d16_hi v9, v2 offset:2448
	v_add_f32_e32 v93, v93, v79
	v_sub_f32_e32 v93, v93, v63
	v_fma_f32 v4, v93, s50, -v79
	v_add_f32_e32 v93, v93, v80
	v_sub_f32_e32 v93, v93, v64
	v_fma_f32 v5, v93, s50, -v80
	v_cvt_pk_bf16_f32 v4, v4, v5
	ds_write_b16 v9, v4 offset:2592
	ds_write_b16_d16_hi v9, v4 offset:2736
	v_add_f32_e32 v93, v93, v81
	v_sub_f32_e32 v93, v93, v65
	v_fma_f32 v2, v93, s50, -v81
	v_add_f32_e32 v93, v93, v82
	v_sub_f32_e32 v93, v93, v66
	v_fma_f32 v3, v93, s50, -v82
	v_cvt_pk_bf16_f32 v2, v2, v3
	ds_write_b16 v9, v2 offset:2880
	ds_write_b16_d16_hi v9, v2 offset:3024
	v_add_f32_e32 v93, v93, v83
	v_sub_f32_e32 v93, v93, v67
	v_fma_f32 v4, v93, s50, -v83
	v_add_f32_e32 v93, v93, v84
	v_sub_f32_e32 v93, v93, v68
	v_fma_f32 v5, v93, s50, -v84
	v_cvt_pk_bf16_f32 v4, v4, v5
	ds_write_b16 v9, v4 offset:3168
	ds_write_b16_d16_hi v9, v4 offset:3312
	v_add_f32_e32 v93, v93, v85
	v_sub_f32_e32 v93, v93, v69
	v_fma_f32 v2, v93, s50, -v85
	v_add_f32_e32 v93, v93, v86
	v_sub_f32_e32 v93, v93, v70
	v_fma_f32 v3, v93, s50, -v86
	v_cvt_pk_bf16_f32 v2, v2, v3
	ds_write_b16 v9, v2 offset:3456
	ds_write_b16_d16_hi v9, v2 offset:3600
	v_add_f32_e32 v93, v93, v87
	v_sub_f32_e32 v93, v93, v71
	v_fma_f32 v4, v93, s50, -v87
	v_add_f32_e32 v93, v93, v88
	v_sub_f32_e32 v93, v93, v72
	v_fma_f32 v5, v93, s50, -v88
	v_cvt_pk_bf16_f32 v4, v4, v5
	ds_write_b16 v9, v4 offset:3744
	ds_write_b16_d16_hi v9, v4 offset:3888
	v_add_f32_e32 v93, v93, v89
	v_sub_f32_e32 v93, v93, v73
	v_fma_f32 v2, v93, s50, -v89
	v_add_f32_e32 v93, v93, v90
	v_sub_f32_e32 v93, v93, v74
	v_fma_f32 v3, v93, s50, -v90
	v_cvt_pk_bf16_f32 v2, v2, v3
	ds_write_b16 v9, v2 offset:4032
	ds_write_b16_d16_hi v9, v2 offset:4176
	v_add_f32_e32 v93, v93, v91
	v_sub_f32_e32 v93, v93, v75
	v_fma_f32 v4, v93, s50, -v91
	v_add_f32_e32 v93, v93, v92
	v_sub_f32_e32 v93, v93, v76
	v_fma_f32 v5, v93, s50, -v92
	v_cvt_pk_bf16_f32 v4, v4, v5
	ds_write_b16 v9, v4 offset:4320
	ds_write_b16_d16_hi v9, v4 offset:4464
	v_and_b32_e32 v2, 31, v0
	v_lshrrev_b32_e32 v3, 5, v0
	v_bfe_u32 v4, v0, 1, 3
	v_xor_b32_e32 v3, v3, v4
	v_lshlrev_b32_e32 v2, 7, v2
	v_add_u32_e32 v2, 0x1c000, v2
	v_lshl_add_u32 v5, v3, 4, v2
	v_xor_b32_e32 v4, 2, v3
	v_lshl_add_u32 v4, v4, 4, v2
	v_xor_b32_e32 v88, 4, v3
	v_xor_b32_e32 v3, 6, v3
	v_lshl_add_u32 v3, v3, 4, v2
	v_lshl_add_u32 v2, v88, 4, v2
	s_waitcnt lgkmcnt(0)
	ds_read_b128 v[28:31], v5 offset:0
	ds_read_b128 v[32:35], v5 offset:4096
	ds_read_b128 v[78:81], v44 offset:0
	ds_read_b128 v[82:85], v44 offset:32
	ds_read_b128 v[86:89], v44 offset:64
	ds_read_b128 v[90:93], v44 offset:96
	ds_read_b128 v[36:39], v4 offset:0
	ds_read_b128 v[40:43], v4 offset:4096
	s_waitcnt lgkmcnt(0)
	v_mfma_f32_32x32x16_bf16 v[46:61], v[28:31], v[78:81], 0
	v_mfma_f32_32x32x16_bf16 v[62:77], v[32:35], v[78:81], 0
	ds_read_b128 v[28:31], v2 offset:0
	ds_read_b128 v[32:35], v2 offset:4096
	v_mfma_f32_32x32x16_bf16 v[46:61], v[36:39], v[82:85], v[46:61]
	v_mfma_f32_32x32x16_bf16 v[62:77], v[40:43], v[82:85], v[62:77]
	ds_read_b128 v[36:39], v3 offset:0
	ds_read_b128 v[40:43], v3 offset:4096
	s_waitcnt lgkmcnt(2)
	v_mfma_f32_32x32x16_bf16 v[46:61], v[28:31], v[86:89], v[46:61]
	v_mfma_f32_32x32x16_bf16 v[62:77], v[32:35], v[86:89], v[62:77]
	s_waitcnt lgkmcnt(0)
	v_mfma_f32_32x32x16_bf16 v[46:61], v[36:39], v[90:93], v[46:61]
	v_mfma_f32_32x32x16_bf16 v[62:77], v[40:43], v[90:93], v[62:77]
	v_lshl_add_u64 v[4:5], s[52:53], 0, v[10:11]
	v_lshl_add_u64 v[98:99], s[52:53], 0, v[96:97]
	s_nop 14
	s_waitcnt vmcnt(0)
	v_readfirstlane_b32 s100, v128
	s_cmp_lg_u32 s100, 0
	s_cbranch_scc1 .Lpf_skip_pool
	v_readlane_b32 s100, v250, 11
	v_readlane_b32 s101, v250, 12
	s_mov_b64 s[56:57], exec
	s_mov_b64 exec, 1
	v_mov_b32_e32 v255, 1
	s_nop 4
	global_atomic_add v255, v1, v255, s[100:101] sc0
	s_mov_b64 exec, s[56:57]
	s_mov_b32 s99, 1
.Lpf_skip_pool:
	v_permlane32_swap_b32 v12, v14
	v_permlane32_swap_b32 v13, v15
	v_permlane32_swap_b32 v16, v18
	v_permlane32_swap_b32 v17, v19
	v_permlane32_swap_b32 v20, v22
	v_permlane32_swap_b32 v21, v23
	v_permlane32_swap_b32 v24, v26
	v_permlane32_swap_b32 v25, v27
	s_mov_b32 s56, 0xbfb8aa3b
	s_mov_b32 s57, 0xbfb8aa3b
	s_mov_b32 s54, 1.0
	s_mov_b32 s55, 1.0
	v_lshlrev_b32_e32 v78, 16, v12
	v_and_b32_e32 v79, 0xffff0000, v12
	v_lshlrev_b32_e32 v80, 16, v13
	v_and_b32_e32 v81, 0xffff0000, v13
	v_lshlrev_b32_e32 v82, 16, v14
	v_and_b32_e32 v83, 0xffff0000, v14
	v_lshlrev_b32_e32 v84, 16, v15
	v_and_b32_e32 v85, 0xffff0000, v15
	v_lshlrev_b32_e32 v86, 16, v16
	v_and_b32_e32 v87, 0xffff0000, v16
	v_lshlrev_b32_e32 v88, 16, v17
	v_and_b32_e32 v89, 0xffff0000, v17
	v_lshlrev_b32_e32 v90, 16, v18
	v_and_b32_e32 v91, 0xffff0000, v18
	v_lshlrev_b32_e32 v92, 16, v19
	v_and_b32_e32 v93, 0xffff0000, v19
	v_pk_mul_f32 v[28:29], v[78:79], s[56:57]
	v_pk_mul_f32 v[30:31], v[80:81], s[56:57]
	v_pk_mul_f32 v[32:33], v[82:83], s[56:57]
	v_pk_mul_f32 v[34:35], v[84:85], s[56:57]
	v_pk_mul_f32 v[36:37], v[86:87], s[56:57]
	v_pk_mul_f32 v[38:39], v[88:89], s[56:57]
	v_pk_mul_f32 v[40:41], v[90:91], s[56:57]
	v_pk_mul_f32 v[42:43], v[92:93], s[56:57]
	v_exp_f32_e32 v28, v28
	v_exp_f32_e32 v29, v29
	v_exp_f32_e32 v30, v30
	v_exp_f32_e32 v31, v31
	v_exp_f32_e32 v32, v32
	v_exp_f32_e32 v33, v33
	v_exp_f32_e32 v34, v34
	v_exp_f32_e32 v35, v35
	v_exp_f32_e32 v36, v36
	v_exp_f32_e32 v37, v37
	v_exp_f32_e32 v38, v38
	v_exp_f32_e32 v39, v39
	v_exp_f32_e32 v40, v40
	v_exp_f32_e32 v41, v41
	v_exp_f32_e32 v42, v42
	v_exp_f32_e32 v43, v43
	v_pk_add_f32 v[28:29], v[28:29], s[54:55]
	v_pk_add_f32 v[30:31], v[30:31], s[54:55]
	v_pk_add_f32 v[32:33], v[32:33], s[54:55]
	v_pk_add_f32 v[34:35], v[34:35], s[54:55]
	v_pk_add_f32 v[36:37], v[36:37], s[54:55]
	v_pk_add_f32 v[38:39], v[38:39], s[54:55]
	v_pk_add_f32 v[40:41], v[40:41], s[54:55]
	v_pk_add_f32 v[42:43], v[42:43], s[54:55]
	v_rcp_f32_e32 v28, v28
	v_rcp_f32_e32 v29, v29
	v_rcp_f32_e32 v30, v30
	v_rcp_f32_e32 v31, v31
	v_rcp_f32_e32 v32, v32
	v_rcp_f32_e32 v33, v33
	v_rcp_f32_e32 v34, v34
	v_rcp_f32_e32 v35, v35
	v_rcp_f32_e32 v36, v36
	v_rcp_f32_e32 v37, v37
	v_rcp_f32_e32 v38, v38
	v_rcp_f32_e32 v39, v39
	v_rcp_f32_e32 v40, v40
	v_rcp_f32_e32 v41, v41
	v_rcp_f32_e32 v42, v42
	v_rcp_f32_e32 v43, v43
	v_pk_mul_f32 v[28:29], v[78:79], v[28:29]
	v_pk_mul_f32 v[30:31], v[80:81], v[30:31]
	v_pk_mul_f32 v[32:33], v[82:83], v[32:33]
	v_pk_mul_f32 v[34:35], v[84:85], v[34:35]
	v_pk_mul_f32 v[36:37], v[86:87], v[36:37]
	v_pk_mul_f32 v[38:39], v[88:89], v[38:39]
	v_pk_mul_f32 v[40:41], v[90:91], v[40:41]
	v_pk_mul_f32 v[42:43], v[92:93], v[42:43]
	v_pk_mul_f32 v[28:29], v[46:47], v[28:29]
	v_pk_mul_f32 v[30:31], v[48:49], v[30:31]
	v_pk_mul_f32 v[32:33], v[50:51], v[32:33]
	v_pk_mul_f32 v[34:35], v[52:53], v[34:35]
	v_pk_mul_f32 v[36:37], v[54:55], v[36:37]
	v_pk_mul_f32 v[38:39], v[56:57], v[38:39]
	v_pk_mul_f32 v[40:41], v[58:59], v[40:41]
	v_pk_mul_f32 v[42:43], v[60:61], v[42:43]
	v_cvt_pk_bf16_f32 v78, v28, v29
	v_cvt_pk_bf16_f32 v79, v30, v31
	v_cvt_pk_bf16_f32 v80, v32, v33
	v_cvt_pk_bf16_f32 v81, v34, v35
	v_cvt_pk_bf16_f32 v82, v36, v37
	v_cvt_pk_bf16_f32 v83, v38, v39
	v_cvt_pk_bf16_f32 v84, v40, v41
	v_cvt_pk_bf16_f32 v85, v42, v43
	s_nop 1
	v_permlane32_swap_b32 v78, v80
	v_permlane32_swap_b32 v79, v81
	v_permlane32_swap_b32 v82, v84
	v_permlane32_swap_b32 v83, v85
	global_store_dwordx4 v[98:99], v[78:81], off offset:384
	global_store_dwordx4 v[98:99], v[82:85], off offset:416
	s_nop 1
	v_lshlrev_b32_e32 v78, 16, v20
	v_and_b32_e32 v79, 0xffff0000, v20
	v_lshlrev_b32_e32 v80, 16, v21
	v_and_b32_e32 v81, 0xffff0000, v21
	v_lshlrev_b32_e32 v82, 16, v22
	v_and_b32_e32 v83, 0xffff0000, v22
	v_lshlrev_b32_e32 v84, 16, v23
	v_and_b32_e32 v85, 0xffff0000, v23
	v_lshlrev_b32_e32 v86, 16, v24
	v_and_b32_e32 v87, 0xffff0000, v24
	v_lshlrev_b32_e32 v88, 16, v25
	v_and_b32_e32 v89, 0xffff0000, v25
	v_lshlrev_b32_e32 v90, 16, v26
	v_and_b32_e32 v91, 0xffff0000, v26
	v_lshlrev_b32_e32 v92, 16, v27
	v_and_b32_e32 v93, 0xffff0000, v27
	v_pk_mul_f32 v[28:29], v[78:79], s[56:57]
	v_pk_mul_f32 v[30:31], v[80:81], s[56:57]
	v_pk_mul_f32 v[32:33], v[82:83], s[56:57]
	v_pk_mul_f32 v[34:35], v[84:85], s[56:57]
	v_pk_mul_f32 v[36:37], v[86:87], s[56:57]
	v_pk_mul_f32 v[38:39], v[88:89], s[56:57]
	v_pk_mul_f32 v[40:41], v[90:91], s[56:57]
	v_pk_mul_f32 v[42:43], v[92:93], s[56:57]
	v_exp_f32_e32 v28, v28
	v_exp_f32_e32 v29, v29
	v_exp_f32_e32 v30, v30
	v_exp_f32_e32 v31, v31
	v_exp_f32_e32 v32, v32
	v_exp_f32_e32 v33, v33
	v_exp_f32_e32 v34, v34
	v_exp_f32_e32 v35, v35
	v_exp_f32_e32 v36, v36
	v_exp_f32_e32 v37, v37
	v_exp_f32_e32 v38, v38
	v_exp_f32_e32 v39, v39
	v_exp_f32_e32 v40, v40
	v_exp_f32_e32 v41, v41
	v_exp_f32_e32 v42, v42
	v_exp_f32_e32 v43, v43
	v_pk_add_f32 v[28:29], v[28:29], s[54:55]
	v_pk_add_f32 v[30:31], v[30:31], s[54:55]
	v_pk_add_f32 v[32:33], v[32:33], s[54:55]
	v_pk_add_f32 v[34:35], v[34:35], s[54:55]
	v_pk_add_f32 v[36:37], v[36:37], s[54:55]
	v_pk_add_f32 v[38:39], v[38:39], s[54:55]
	v_pk_add_f32 v[40:41], v[40:41], s[54:55]
	v_pk_add_f32 v[42:43], v[42:43], s[54:55]
	v_rcp_f32_e32 v28, v28
	v_rcp_f32_e32 v29, v29
	v_rcp_f32_e32 v30, v30
	v_rcp_f32_e32 v31, v31
	v_rcp_f32_e32 v32, v32
	v_rcp_f32_e32 v33, v33
	v_rcp_f32_e32 v34, v34
	v_rcp_f32_e32 v35, v35
	v_rcp_f32_e32 v36, v36
	v_rcp_f32_e32 v37, v37
	v_rcp_f32_e32 v38, v38
	v_rcp_f32_e32 v39, v39
	v_rcp_f32_e32 v40, v40
	v_rcp_f32_e32 v41, v41
	v_rcp_f32_e32 v42, v42
	v_rcp_f32_e32 v43, v43
	v_pk_mul_f32 v[28:29], v[78:79], v[28:29]
	v_pk_mul_f32 v[30:31], v[80:81], v[30:31]
	v_pk_mul_f32 v[32:33], v[82:83], v[32:33]
	v_pk_mul_f32 v[34:35], v[84:85], v[34:35]
	v_pk_mul_f32 v[36:37], v[86:87], v[36:37]
	v_pk_mul_f32 v[38:39], v[88:89], v[38:39]
	v_pk_mul_f32 v[40:41], v[90:91], v[40:41]
	v_pk_mul_f32 v[42:43], v[92:93], v[42:43]
	v_pk_mul_f32 v[28:29], v[62:63], v[28:29]
	v_pk_mul_f32 v[30:31], v[64:65], v[30:31]
	v_pk_mul_f32 v[32:33], v[66:67], v[32:33]
	v_pk_mul_f32 v[34:35], v[68:69], v[34:35]
	v_pk_mul_f32 v[36:37], v[70:71], v[36:37]
	v_pk_mul_f32 v[38:39], v[72:73], v[38:39]
	v_pk_mul_f32 v[40:41], v[74:75], v[40:41]
	v_pk_mul_f32 v[42:43], v[76:77], v[42:43]
	v_cvt_pk_bf16_f32 v78, v28, v29
	v_cvt_pk_bf16_f32 v79, v30, v31
	v_cvt_pk_bf16_f32 v80, v32, v33
	v_cvt_pk_bf16_f32 v81, v34, v35
	v_cvt_pk_bf16_f32 v82, v36, v37
	v_cvt_pk_bf16_f32 v83, v38, v39
	v_cvt_pk_bf16_f32 v84, v40, v41
	v_cvt_pk_bf16_f32 v85, v42, v43
	s_nop 1
	v_permlane32_swap_b32 v78, v80
	v_permlane32_swap_b32 v79, v81
	v_permlane32_swap_b32 v82, v84
	v_permlane32_swap_b32 v83, v85
	global_store_dwordx4 v[98:99], v[78:81], off offset:448
	global_store_dwordx4 v[98:99], v[82:85], off offset:480
	s_waitcnt vmcnt(0)
	s_mov_b32 m0, s59
	v_readlane_b32 s38, v250, 39
	v_readlane_b32 s39, v250, 40
	s_barrier
